# P11 (LN2 layer 0) LDS parameter fill: pointers via s_load, all 4 then all 6 data loads issued together with one wait each, instead of 14 dependent load-wait steps
# baseline (speedup 1.0000x reference)
.LBB0_1812:
	s_cmp_lt_i32 s56, 12
	s_cselect_b64 s[6:7], -1, 0
	s_and_b64 s[8:9], s[6:7], s[8:9]
	s_andn2_b64 vcc, exec, s[8:9]
	s_cbranch_vccnz .LBB0_1849
	s_load_dword s31, s[0:1], 0x100
	s_waitcnt vmcnt(0)
	v_mbcnt_hi_u32_b32 v4, -1, v254
	v_mov_b32_e32 v5, v4
	s_waitcnt lgkmcnt(0)
	s_mul_i32 s30, s31, s2
	s_cmpk_gt_i32 s30, 0x2fff
	s_cbranch_scc1 .LBB0_1849
	s_load_dwordx2 s[16:17], s[0:1], 0xf0
	s_and_b32 s3, s90, 0xffffffc0
	v_add_u32_e32 v6, s3, v5
	s_movk_i32 s3, 0x800
	v_cmp_gt_i32_e32 vcc, s3, v6
	v_lshlrev_b32_e32 v7, 2, v5
	s_and_saveexec_b64 s[6:7], vcc
	s_cbranch_execz .LBB0_1827
	s_load_dwordx2 s[10:11], s[0:1], 0xa8
	s_load_dwordx2 s[12:13], s[0:1], 0xb0
	s_load_dwordx2 s[14:15], s[0:1], 0xd8
	s_load_dwordx2 s[18:19], s[0:1], 0xe0
	v_lshl_add_u32 v8, s33, 8, v7
	v_mov_b32_e32 v1, 0
	v_lshlrev_b32_e32 v0, 2, v8
	v_and_b32_e32 v0, 0x1ff0, v0
	s_waitcnt lgkmcnt(0)
	v_lshl_add_u64 v[230:231], s[10:11], 0, v[0:1]
	v_lshl_add_u64 v[232:233], s[12:13], 0, v[0:1]
	v_lshl_add_u64 v[234:235], s[14:15], 0, v[0:1]
	v_lshl_add_u64 v[236:237], s[18:19], 0, v[0:1]
	global_load_dwordx4 v[206:209], v[230:231], off
	global_load_dwordx4 v[210:213], v[232:233], off
	global_load_dwordx4 v[214:217], v[234:235], off
	global_load_dwordx4 v[218:221], v[236:237], off
	s_waitcnt vmcnt(0)
	ds_write_b128 v0, v[206:209]
	ds_write_b128 v0, v[210:213] offset:8192
	ds_write_b128 v0, v[214:217] offset:16384
	ds_write_b128 v0, v[218:221] offset:24576
.LBB0_1827:
	s_or_b64 exec, exec, s[6:7]
	s_add_i32 s3, s30, 0xfffff000
	s_lshr_b32 s3, s3, 10
	s_add_i32 s3, s3, 1
	s_cmpk_gt_i32 s30, 0xfff
	s_movk_i32 s6, 0xc00
	s_cselect_b32 s3, s3, 0
	v_cmp_gt_i32_e32 vcc, s6, v6
	s_and_saveexec_b64 s[6:7], vcc
	s_cbranch_execz .LBB0_1834
	s_waitcnt lgkmcnt(0)
	s_min_i32 s10, s3, 8
	s_add_i32 s11, s3, 1
	s_min_i32 s11, s11, 8
	s_mul_i32 s10, s10, 0xc000
	s_mul_i32 s11, s11, 0xc000
	s_add_u32 s12, s16, 0x10a000
	s_addc_u32 s13, s17, 0
	s_add_u32 s14, s16, 0x16c000
	s_addc_u32 s15, s17, 0
	s_add_u32 s18, s12, s10
	s_addc_u32 s19, s13, 0
	s_add_u32 s20, s14, s10
	s_addc_u32 s21, s15, 0
	s_add_u32 s22, s12, s11
	s_addc_u32 s23, s13, 0
	s_add_u32 s24, s14, s11
	s_addc_u32 s25, s15, 0
	v_lshl_add_u32 v8, s33, 8, v7
	v_mov_b32_e32 v1, 0
	v_lshlrev_b32_e32 v0, 2, v8
	v_and_b32_e32 v0, 0x1ff0, v0
	v_lshl_add_u64 v[230:231], s[18:19], 0, v[0:1]
	v_lshl_add_u64 v[232:233], s[20:21], 0, v[0:1]
	v_lshl_add_u64 v[234:235], s[22:23], 0, v[0:1]
	v_lshl_add_u64 v[236:237], s[24:25], 0, v[0:1]
	v_add_co_u32_e32 v238, vcc, 0x2000, v232
	s_nop 1
	v_addc_co_u32_e32 v239, vcc, 0, v233, vcc
	v_add_co_u32_e32 v240, vcc, 0x2000, v236
	s_nop 1
	v_addc_co_u32_e32 v241, vcc, 0, v237, vcc
	global_load_dwordx4 v[206:209], v[230:231], off
	global_load_dwordx4 v[210:213], v[232:233], off
	global_load_dwordx4 v[214:217], v[238:239], off
	global_load_dwordx4 v[218:221], v[234:235], off
	global_load_dwordx4 v[222:225], v[236:237], off
	global_load_dwordx4 v[226:229], v[240:241], off
	v_add_u32_e32 v2, 0x8000, v0
	s_waitcnt vmcnt(0)
	ds_write_b128 v0, v[206:209] offset:32768
	ds_write_b128 v0, v[210:213] offset:40960
	ds_write_b128 v0, v[214:217] offset:49152
	ds_write_b128 v0, v[218:221] offset:57344
	ds_write_b128 v2, v[222:225] offset:32768
	ds_write_b128 v2, v[226:229] offset:40960
